# grid barrier first-use census: the 16 per-XCD counter loads issued back to back with one wait instead of a load-wait-add chain
# speedup vs baseline: 1.0015x; 1.0015x over previous
.LBB0_32:
	v_readlane_b32 s4, v251, 8
	v_readlane_b32 s5, v251, 9
	s_mov_b64 s[6:7], -1
	s_waitcnt lgkmcnt(0)
	s_nop 4
	global_load_dword v0, v145, s[4:5] sc1
	v_readlane_b32 s4, v251, 10
	v_readlane_b32 s5, v251, 11
	s_nop 4
	global_load_dword v1, v145, s[4:5] sc1
	v_readlane_b32 s4, v251, 12
	v_readlane_b32 s5, v251, 13
	s_nop 4
	global_load_dword v2, v145, s[4:5] sc1
	v_readlane_b32 s4, v251, 14
	v_readlane_b32 s5, v251, 15
	s_nop 4
	global_load_dword v3, v145, s[4:5] sc1
	v_readlane_b32 s4, v251, 16
	v_readlane_b32 s5, v251, 17
	s_nop 4
	global_load_dword v4, v145, s[4:5] sc1
	v_readlane_b32 s4, v251, 18
	v_readlane_b32 s5, v251, 19
	s_nop 4
	global_load_dword v5, v145, s[4:5] sc1
	v_readlane_b32 s4, v251, 20
	v_readlane_b32 s5, v251, 21
	s_nop 4
	global_load_dword v6, v145, s[4:5] sc1
	v_readlane_b32 s4, v251, 22
	v_readlane_b32 s5, v251, 23
	s_nop 4
	global_load_dword v7, v145, s[4:5] sc1
	v_readlane_b32 s4, v251, 24
	v_readlane_b32 s5, v251, 25
	s_nop 4
	global_load_dword v8, v145, s[4:5] sc1
	v_readlane_b32 s4, v251, 26
	v_readlane_b32 s5, v251, 27
	s_nop 4
	global_load_dword v9, v145, s[4:5] sc1
	v_readlane_b32 s4, v251, 28
	v_readlane_b32 s5, v251, 29
	s_nop 4
	global_load_dword v10, v145, s[4:5] sc1
	v_readlane_b32 s4, v251, 30
	v_readlane_b32 s5, v251, 31
	s_nop 4
	global_load_dword v11, v145, s[4:5] sc1
	v_readlane_b32 s4, v251, 32
	v_readlane_b32 s5, v251, 33
	s_nop 4
	global_load_dword v12, v145, s[4:5] sc1
	v_readlane_b32 s4, v251, 34
	v_readlane_b32 s5, v251, 35
	s_nop 4
	global_load_dword v13, v145, s[4:5] sc1
	v_readlane_b32 s4, v251, 36
	v_readlane_b32 s5, v251, 37
	s_nop 4
	global_load_dword v14, v145, s[4:5] sc1
	v_readlane_b32 s4, v251, 38
	v_readlane_b32 s5, v251, 39
	s_nop 4
	global_load_dword v15, v145, s[4:5] sc1
	s_mov_b64 s[4:5], -1
	s_waitcnt vmcnt(0)
	v_add_u32_e32 v16, v1, v0
	v_add_u32_e32 v16, v16, v2
	v_add_u32_e32 v16, v16, v3
	v_add_u32_e32 v16, v16, v4
	v_add_u32_e32 v16, v16, v5
	v_add_u32_e32 v16, v16, v6
	v_add_u32_e32 v16, v16, v7
	v_add_u32_e32 v16, v16, v8
	v_add_u32_e32 v16, v16, v9
	v_add_u32_e32 v16, v16, v10
	v_add_u32_e32 v16, v16, v11
	v_add_u32_e32 v16, v16, v12
	v_add_u32_e32 v16, v16, v13
	v_add_u32_e32 v16, v16, v14
	v_add_u32_e32 v16, v16, v15
	v_cmp_eq_u32_e32 vcc, s97, v16
	s_cbranch_vccnz .LBB0_31
	s_and_b32 s4, s10, 0xff
	s_cmp_eq_u32 s4, 0
	s_mov_b64 s[4:5], -1
	s_mov_b64 s[8:9], -1
	s_sleep 1
	s_cbranch_scc1 .LBB0_36
	s_and_b64 vcc, exec, s[8:9]
	s_cbranch_vccz .LBB0_31
